# speedup vs baseline: 1.0149x; 1.0050x over previous
; __device__ __forceinline__ void unpark_fma(f32x16* o, const char* pk, int lane, const f32x4* f4) {
; #pragma unroll
;   for (int d0 = 0; d0 < 4; ++d0)
; #pragma unroll
;     for (int a = 0; a < 4; ++a) { const u32x2 w = *reinterpret_cast<const u32x2*>(pk + ((d0 * 4 + a) * 64 + lane) * 8);
;       o[d0][4 * a + 0] = fmaf(o[d0][4 * a + 0], f4[a][0], __uint_as_float(w[0] << 16));
;       o[d0][4 * a + 1] = fmaf(o[d0][4 * a + 1], f4[a][1], __uint_as_float(w[0] & 0xffff0000u));
;       o[d0][4 * a + 2] = fmaf(o[d0][4 * a + 2], f4[a][2], __uint_as_float(w[1] << 16));
;       o[d0][4 * a + 3] = fmaf(o[d0][4 * a + 3], f4[a][3], __uint_as_float(w[1] & 0xffff0000u)); }
; template <int MODE>
; __device__ __forceinline__ void nsa_single(const Params& p, const LaneId& L, int q0, int g, int ntiles, int first, char* smem, const bf16x8* qr, float gate, f32x16* o) {
;     ...
;   l = half_swap_sum(l);
;   { const float f = (l > 0.f) ? gate / l : 0.f; f32x4 f4[4]; row_bcast(fac, L, f, f4); unpark_fma(o, pk, L.lane, f4); }
;   __syncthreads();
.LBB0_339:
	s_or_b64 exec, exec, s[8:9]
	v_add_u32_e32 v2, v141, v142
	ds_read2st64_b64 v[84:87], v2 offset1:1
	ds_read_b128 v[80:83], v146
	ds_read_b128 v[76:79], v146 offset:32
	ds_read_b128 v[72:75], v146 offset:64
	ds_read_b128 v[68:71], v146 offset:96
	ds_read2st64_b64 v[88:91], v2 offset0:2 offset1:3
	s_waitcnt lgkmcnt(0)
	v_lshlrev_b32_e32 v92, 16, v84
	v_and_b32_e32 v93, 0xffff0000, v84
	v_lshlrev_b32_e32 v84, 16, v85
	v_and_b32_e32 v85, 0xffff0000, v85
	v_pk_fma_f32 v[84:85], v[54:55], v[82:83], v[84:85]
	v_lshlrev_b32_e32 v54, 16, v86
	v_and_b32_e32 v55, 0xffff0000, v86
	v_pk_fma_f32 v[54:55], v[56:57], v[76:77], v[54:55]
	v_lshlrev_b32_e32 v56, 16, v87
	v_and_b32_e32 v57, 0xffff0000, v87
	v_pk_fma_f32 v[56:57], v[58:59], v[78:79], v[56:57]
	v_lshlrev_b32_e32 v58, 16, v88
	v_and_b32_e32 v59, 0xffff0000, v88
	v_pk_fma_f32 v[58:59], v[60:61], v[72:73], v[58:59]
	v_lshlrev_b32_e32 v60, 16, v89
	v_and_b32_e32 v61, 0xffff0000, v89
	ds_read2st64_b64 v[86:89], v2 offset0:4 offset1:5
	v_pk_fma_f32 v[60:61], v[62:63], v[74:75], v[60:61]
	v_lshlrev_b32_e32 v62, 16, v90
	v_and_b32_e32 v63, 0xffff0000, v90
	v_pk_fma_f32 v[52:53], v[52:53], v[80:81], v[92:93]
	v_pk_fma_f32 v[62:63], v[64:65], v[68:69], v[62:63]
	v_lshlrev_b32_e32 v64, 16, v91
	v_and_b32_e32 v65, 0xffff0000, v91
	ds_read2st64_b64 v[90:93], v2 offset0:6 offset1:7
	v_pk_fma_f32 v[64:65], v[66:67], v[70:71], v[64:65]
	s_waitcnt lgkmcnt(0)
	v_lshlrev_b32_e32 v66, 16, v86
	v_and_b32_e32 v67, 0xffff0000, v86
	v_pk_fma_f32 v[66:67], v[36:37], v[80:81], v[66:67]
	v_lshlrev_b32_e32 v36, 16, v87
	v_and_b32_e32 v37, 0xffff0000, v87
	v_pk_fma_f32 v[86:87], v[38:39], v[82:83], v[36:37]
	v_lshlrev_b32_e32 v36, 16, v88
	v_and_b32_e32 v37, 0xffff0000, v88
	v_pk_fma_f32 v[94:95], v[40:41], v[76:77], v[36:37]
	v_lshlrev_b32_e32 v36, 16, v89
	v_and_b32_e32 v37, 0xffff0000, v89
	v_pk_fma_f32 v[88:89], v[42:43], v[78:79], v[36:37]
	v_lshlrev_b32_e32 v36, 16, v90
	v_and_b32_e32 v37, 0xffff0000, v90
	v_pk_fma_f32 v[44:45], v[44:45], v[72:73], v[36:37]
	v_lshlrev_b32_e32 v36, 16, v91
	v_and_b32_e32 v37, 0xffff0000, v91
	v_pk_fma_f32 v[46:47], v[46:47], v[74:75], v[36:37]
	v_lshlrev_b32_e32 v36, 16, v92
	v_and_b32_e32 v37, 0xffff0000, v92
	v_pk_fma_f32 v[48:49], v[48:49], v[68:69], v[36:37]
	ds_read2st64_b64 v[36:39], v2 offset0:8 offset1:9
	v_lshlrev_b32_e32 v40, 16, v93
	v_and_b32_e32 v41, 0xffff0000, v93
	v_pk_fma_f32 v[50:51], v[50:51], v[70:71], v[40:41]
	ds_read2st64_b64 v[40:43], v2 offset0:10 offset1:11
	s_waitcnt lgkmcnt(0)
	v_lshlrev_b32_e32 v90, 16, v36
	v_and_b32_e32 v91, 0xffff0000, v36
	v_pk_fma_f32 v[90:91], v[20:21], v[80:81], v[90:91]
	v_lshlrev_b32_e32 v20, 16, v37
	v_and_b32_e32 v21, 0xffff0000, v37
	v_pk_fma_f32 v[36:37], v[22:23], v[82:83], v[20:21]
	v_lshlrev_b32_e32 v20, 16, v38
	v_and_b32_e32 v21, 0xffff0000, v38
	v_pk_fma_f32 v[92:93], v[24:25], v[76:77], v[20:21]
	v_lshlrev_b32_e32 v20, 16, v39
	v_and_b32_e32 v21, 0xffff0000, v39
	v_pk_fma_f32 v[38:39], v[26:27], v[78:79], v[20:21]
	v_lshlrev_b32_e32 v20, 16, v40
	v_and_b32_e32 v21, 0xffff0000, v40
	v_pk_fma_f32 v[28:29], v[28:29], v[72:73], v[20:21]
	v_lshlrev_b32_e32 v20, 16, v41
	v_and_b32_e32 v21, 0xffff0000, v41
	v_pk_fma_f32 v[30:31], v[30:31], v[74:75], v[20:21]
	v_lshlrev_b32_e32 v20, 16, v42
	v_and_b32_e32 v21, 0xffff0000, v42
	v_pk_fma_f32 v[32:33], v[32:33], v[68:69], v[20:21]
	ds_read2st64_b64 v[20:23], v2 offset0:12 offset1:13
	v_lshlrev_b32_e32 v24, 16, v43
	v_and_b32_e32 v25, 0xffff0000, v43
	v_pk_fma_f32 v[34:35], v[34:35], v[70:71], v[24:25]
	ds_read2st64_b64 v[24:27], v2 offset0:14 offset1:15
	s_waitcnt lgkmcnt(0)
	v_lshlrev_b32_e32 v40, 16, v20
	v_and_b32_e32 v41, 0xffff0000, v20
	v_lshlrev_b32_e32 v20, 16, v21
	v_and_b32_e32 v21, 0xffff0000, v21
	v_pk_fma_f32 v[6:7], v[6:7], v[82:83], v[20:21]
	v_lshlrev_b32_e32 v20, 16, v22
	v_and_b32_e32 v21, 0xffff0000, v22
	v_pk_fma_f32 v[8:9], v[8:9], v[76:77], v[20:21]
	v_lshlrev_b32_e32 v20, 16, v23
	v_and_b32_e32 v21, 0xffff0000, v23
	v_pk_fma_f32 v[10:11], v[10:11], v[78:79], v[20:21]
	v_lshlrev_b32_e32 v20, 16, v24
	v_and_b32_e32 v21, 0xffff0000, v24
	v_pk_fma_f32 v[12:13], v[12:13], v[72:73], v[20:21]
	v_lshlrev_b32_e32 v20, 16, v25
	v_and_b32_e32 v21, 0xffff0000, v25
	v_mov_b32_e32 v142, v1
	v_pk_fma_f32 v[14:15], v[14:15], v[74:75], v[20:21]
	v_lshlrev_b32_e32 v20, 16, v26
	v_and_b32_e32 v21, 0xffff0000, v26
	s_waitcnt vmcnt(0)
	s_barrier
; __device__ __forceinline__ int v_rd_base(int lane) { return ((lane & 3) << 3) | (((lane >> 2) & 3) << 6) | (((lane >> 4) & 1) << 5) | (((lane >> 5) & 1) << 8); }
; __device__ __forceinline__ float gate_of(const Params& p, const LaneId& L, int b) { return sigmoid_f(ldbf(p32(p.P, (unsigned)(L.tq * LDP + C_GT + L.h * 3 + b)))); }
; template <int MODE>
; __device__ __forceinline__ void nsa_single(const Params& p, const LaneId& L, int q0, int g, int ntiles, int first, char* smem, const bf16x8* qr, float gate, f32x16* o) {
;     ...
;   if (MODE == 1) { Kg = p.kvh + (long)(0 + g) * T * 128; Vg = p.kvh + (long)(4 + g) * T * 128; }
;   else { Kg = p.kvh + (long)(8 + g) * T * 128; Vg = p.kvh + (long)(12 + g) * T * 128; }
;   auto tile_row = [&](int i) -> int { const int ii = ntiles - 1 - i; if (MODE == 1) return __builtin_amdgcn_readfirstlane((int)ulist[ii]) * 64; return q0 - 512 + 64 * (first + ii); };
;   const int vb0 = (int)(uintptr_t)(smem + NSA_V0) + v_rd_base(L.lane);
;   float m = -1e30f, l = 0.f;
;   if (ntiles > 0) { const int row = tile_row(0); dma_k(Kg + (long)row * ld, ld, smem + NSA_K0, L.tid); dma_v(Vg + (long)row * ld, ld, smem + NSA_V0, L.tid); }
; __device__ void nsa_item(const Params& p, int qb, int g, char* smem) {
;     ...
;     const LaneId L = lane_id(q0, g);
;     park_o(o, smem + NSA_IMP + L.wid * 8192, L.lane);
; #pragma unroll
;     for (int d0 = 0; d0 < 4; ++d0) o[d0] = f32x16{};
;     const int first = (qb < 8) ? 8 - qb : 0;
;     nsa_single<2>(p, L, q0, g, 9 - first, first, smem, qr, gate_of(p, L, 2), o);
	v_pk_fma_f32 v[16:17], v[16:17], v[68:69], v[20:21]
	v_and_b32_e32 v26, 3, v142
	v_lshlrev_b32_e32 v20, 16, v27
	v_and_b32_e32 v21, 0xffff0000, v27
	v_ashrrev_i32_e32 v24, 6, v142
	v_or_b32_e32 v27, s17, v26
	v_pk_fma_f32 v[4:5], v[4:5], v[80:81], v[40:41]
	v_and_b32_e32 v25, 63, v142
	v_add_u32_e32 v2, 1, v27
	v_lshlrev_b32_e32 v42, 3, v24
	v_cvt_f32_u32_e32 v40, v2
	v_add_u32_e32 v2, s5, v42
	v_lshl_add_u32 v144, v24, 13, v179
	v_lshlrev_b32_e32 v145, 3, v25
	v_cvt_pk_bf16_f32 v4, v4, v5
	v_cvt_pk_bf16_f32 v5, v6, v7
	v_cvt_pk_bf16_f32 v6, v8, v9
	v_bfe_u32 v8, v142, 2, 3
	v_pk_fma_f32 v[18:19], v[18:19], v[70:71], v[20:21]
	v_cvt_pk_bf16_f32 v20, v52, v53
	v_or_b32_e32 v52, v144, v145
	v_cvt_pk_bf16_f32 v7, v10, v11
	v_or_b32_e32 v2, v2, v8
	ds_write2st64_b64 v52, v[4:5], v[6:7] offset0:12 offset1:13
	v_cvt_pk_bf16_f32 v4, v12, v13
	v_cvt_pk_bf16_f32 v5, v14, v15
	v_cvt_pk_bf16_f32 v6, v16, v17
	v_cvt_pk_bf16_f32 v7, v18, v19
	v_mul_lo_u32 v2, v2, s25
	ds_write2st64_b64 v52, v[4:5], v[6:7] offset0:14 offset1:15
	v_mad_u64_u32 v[4:5], s[0:1], v27, 3, v[2:3]
	s_sub_i32 s18, 11, s16
	v_lshl_add_u32 v2, v4, 1, v192
	s_lshl_b64 s[12:13], s[18:19], 22
	global_load_ushort v146, v2, s[46:47]
	s_add_u32 s0, s34, s12
	v_lshrrev_b32_e32 v5, 5, v142
	v_ashrrev_i32_e32 v2, 4, v142
	s_addc_u32 s1, s35, s13
	s_sub_i32 s18, 15, s16
	v_and_b32_e32 v4, 15, v142
	v_and_b32_e32 v6, 8, v5
	v_and_b32_e32 v7, 7, v2
	s_lshl_b64 s[10:11], s[18:19], 22
	v_bitop3_b32 v7, v7, v4, v6 bitop3:0x36
	v_lshlrev_b32_e32 v2, 8, v2
	v_cvt_pk_bf16_f32 v21, v84, v85
	v_cvt_pk_bf16_f32 v22, v54, v55
	v_cvt_pk_bf16_f32 v23, v56, v57
	s_add_u32 s2, s34, s10
	v_lshl_or_b32 v2, v7, 4, v2
	v_add_u32_e32 v7, 0x200, v142
	ds_write2st64_b64 v52, v[20:21], v[22:23] offset1:1
	v_cvt_pk_bf16_f32 v20, v58, v59
	v_cvt_pk_bf16_f32 v21, v60, v61
	v_cvt_pk_bf16_f32 v22, v62, v63
	v_cvt_pk_bf16_f32 v23, v64, v65
	s_addc_u32 s3, s35, s11
	s_lshl_b32 s8, s15, 14
	v_ashrrev_i32_e32 v7, 4, v7
	ds_write2st64_b64 v52, v[20:21], v[22:23] offset0:2 offset1:3
	v_cvt_pk_bf16_f32 v20, v66, v67
	v_cvt_pk_bf16_f32 v21, v86, v87
	v_cvt_pk_bf16_f32 v22, v94, v95
	v_cvt_pk_bf16_f32 v23, v88, v89
	s_add_u32 s0, s0, s8
	v_readfirstlane_b32 s9, v142
	v_and_b32_e32 v9, 7, v7
	ds_write2st64_b64 v52, v[20:21], v[22:23] offset0:4 offset1:5
	v_cvt_pk_bf16_f32 v20, v44, v45
	v_cvt_pk_bf16_f32 v21, v46, v47
	v_cvt_pk_bf16_f32 v22, v48, v49
	v_cvt_pk_bf16_f32 v23, v50, v51
	s_addc_u32 s1, s1, 0
	s_lshl_b32 s9, s9, 4
	v_bitop3_b32 v4, v9, v4, v6 bitop3:0x36
	v_lshlrev_b32_e32 v6, 8, v7
	v_lshrrev_b32_e32 v10, 1, v142
	ds_write2st64_b64 v52, v[20:21], v[22:23] offset0:6 offset1:7
	v_cvt_pk_bf16_f32 v20, v90, v91
	v_cvt_pk_bf16_f32 v21, v36, v37
	v_cvt_pk_bf16_f32 v22, v92, v93
	v_cvt_pk_bf16_f32 v23, v38, v39
	s_and_b32 s9, s9, 0xfffffc00
	v_lshl_or_b32 v4, v4, 4, v6
	v_and_b32_e32 v6, 0x60, v142
	v_lshlrev_b32_e32 v7, 3, v142
	v_lshrrev_b32_e32 v9, 4, v142
	v_and_b32_e32 v10, 8, v10
	ds_write2st64_b64 v52, v[20:21], v[22:23] offset0:8 offset1:9
	v_cvt_pk_bf16_f32 v20, v28, v29
	v_cvt_pk_bf16_f32 v21, v30, v31
	v_cvt_pk_bf16_f32 v22, v32, v33
	v_cvt_pk_bf16_f32 v23, v34, v35
	s_mov_b32 m0, s9
	v_and_or_b32 v6, v7, 24, v6
	v_bfe_u32 v7, v142, 2, 2
	v_and_b32_e32 v5, 4, v5
	v_and_or_b32 v9, v9, 48, v10
	ds_write2st64_b64 v52, v[20:21], v[22:23] offset0:10 offset1:11
	global_load_lds_dwordx4 v2, s[0:1]
	s_add_i32 m0, s9, 0x2000
	v_or3_b32 v5, v5, v7, v9
	global_load_lds_dwordx4 v4, s[0:1]
	s_add_u32 s0, s2, s8
	v_lshlrev_b32_e32 v6, 1, v6
	v_lshlrev_b32_e32 v9, 8, v5
	s_addc_u32 s1, s3, 0
	v_or_b32_e32 v5, v9, v6
	s_add_i32 m0, s9, 0x8000
	s_movk_i32 s2, 0x2000
	global_load_lds_dwordx4 v5, s[0:1]
	v_bitop3_b32 v6, v9, s2, v6 bitop3:0x36
	s_add_i32 m0, s9, 0xa000
	v_mul_f32_e32 v43, -0.5, v40
	global_load_lds_dwordx4 v6, s[0:1]
	s_mov_b32 s0, 0xc2fc0000
	v_cmp_gt_f32_e32 vcc, s0, v43
	v_bfe_u32 v41, v142, 5, 1
	v_lshlrev_b32_e32 v15, 2, v41
	v_cndmask_b32_e32 v5, 0, v180, vcc
; __device__ __forceinline__ int v_rd_base(int lane) { return ((lane & 3) << 3) | (((lane >> 2) & 3) << 6) | (((lane >> 4) & 1) << 5) | (((lane >> 5) & 1) << 8); }
; template <int MODE>
; __device__ __forceinline__ void nsa_single(const Params& p, const LaneId& L, int q0, int g, int ntiles, int first, char* smem, const bf16x8* qr, float gate, f32x16* o) {
;     ...
;   auto tile_row = [&](int i) -> int { const int ii = ntiles - 1 - i; if (MODE == 1) return __builtin_amdgcn_readfirstlane((int)ulist[ii]) * 64; return q0 - 512 + 64 * (first + ii); };
;   const int vb0 = (int)(uintptr_t)(smem + NSA_V0) + v_rd_base(L.lane);
;   float m = -1e30f, l = 0.f;
;   if (ntiles > 0) { const int row = tile_row(0); dma_k(Kg + (long)row * ld, ld, smem + NSA_K0, L.tid); dma_v(Vg + (long)row * ld, ld, smem + NSA_V0, L.tid); }
; #pragma unroll 1
;   for (int i = 0; i < ntiles; ++i) {
;     const int row = tile_row(i), buf = i & 1;
;     char* Kl = smem + NSA_K0 + buf * 16384;
;     asm volatile("s_waitcnt vmcnt(0)" ::: "memory");
;     __syncthreads();
;     if (i + 1 < ntiles) { const int rn = tile_row(i + 1); dma_k(Kg + (long)rn * ld, ld, smem + NSA_K0 + (buf ^ 1) * 16384, L.tid); dma_v(Vg + (long)rn * ld, ld, smem + NSA_V0 + (buf ^ 1) * 16384, L.tid); }
;     int pb = row, lo, hl; float badd = 0.f;
;     if (MODE == 1) { const int j = row >> 6; lo = NEG; const bool fl = ((mysel[j >> 5] >> (j & 31)) & 1u) != 0u;
;       if (row == q0) hl = fl ? (L.tq - pb) : NEG; else { hl = 1000; badd = fl ? 0.f : -INFINITY; } }
;     else { lo = L.tq - 512 - pb; hl = L.tq - pb; }
;     constexpr float C = 0.08838834764831845f * LOG2E;
;     const float A1 = L.sl2; const float B1 = L.sl2 * (float)(pb - L.tq) + A1 * (float)(4 * L.hi) + badd;
;     const int lo2 = lo - 4 * L.hi, hl2 = hl - 4 * L.hi;
	v_fmac_f32_e32 v5, -0.5, v40
	v_exp_f32_e32 v5, v5
	v_cndmask_b32_e32 v7, 0, v181, vcc
	v_cvt_f32_ubyte0_e32 v16, v15
	v_and_or_b32 v10, v142, 7, v10
	v_ldexp_f32 v5, v5, v7
	v_mul_f32_e32 v132, 0x3fb8aa3b, v5
	v_mul_f32_e32 v150, v132, v16
	v_lshlrev_b32_e32 v16, 4, v41
	v_lshlrev_b32_e32 v10, 4, v10
	s_movk_i32 s2, 0x60
	v_bitop3_b32 v155, v10, v16, s2 bitop3:0x1e
	s_movk_i32 s2, 0x80
	v_bitop3_b32 v156, v10, v16, s2 bitop3:0x1e
	s_movk_i32 s2, 0xa0
	v_bitop3_b32 v157, v10, v16, s2 bitop3:0x1e
	s_movk_i32 s2, 0xc0
	v_bitop3_b32 v158, v10, v16, s2 bitop3:0x1e
	s_movk_i32 s2, 0xe0
	v_bitop3_b32 v159, v10, v16, s2 bitop3:0x1e
	s_min_u32 s2, s15, 8
	s_lshl_b32 s24, s2, 14
	s_andn2_b32 s2, 0xff, s14
	v_sub_u32_e64 v5, 8, s15 clamp
	s_addk_i32 s24, 0x4000
	s_lshl_b32 s18, s2, 14
	v_readlane_b32 s14, v252, 51
	v_sub_u32_e32 v149, 9, v5
	v_lshlrev_b32_e32 v5, 4, v142
	s_add_u32 s2, s14, s12
	v_readlane_b32 s12, v252, 52
	v_and_b32_e32 v13, 0xc0, v5
	v_mov_b32_e32 v5, v3
	v_xor_b32_e32 v152, v10, v16
	v_bitop3_b32 v153, v10, v16, 32 bitop3:0x1e
	v_bitop3_b32 v154, v10, v16, 64 bitop3:0x1e
	v_lshlrev_b32_e32 v10, 1, v142
	s_addc_u32 s3, s12, s13
	v_lshl_add_u64 v[134:135], s[2:3], 0, v[2:3]
	v_lshl_add_u64 v[136:137], s[2:3], 0, v[4:5]
	v_and_b32_e32 v2, 0xc0, v10
	v_lshlrev_b32_e32 v4, 4, v26
	s_add_u32 s2, s14, s10
	v_and_b32_e32 v11, 31, v142
	v_lshl_add_u32 v12, v24, 7, v189
	v_and_b32_e32 v14, 0x118, v145
	v_or3_b32 v2, v9, v2, v4
	s_addc_u32 s3, s12, s11
	v_mov_b32_e32 v7, v3
	v_lshlrev_b32_e32 v151, 8, v11
	v_lshl_add_u32 v148, v11, 2, v12
	v_or_b32_e32 v147, v12, v16
	v_and_or_b32 v11, v10, 32, v14
	v_lshl_add_u64 v[138:139], s[2:3], 0, v[2:3]
	v_or_b32_e32 v2, v8, v42
	v_mov_b32_e32 v16, v3
	v_mov_b32_e32 v17, v3
	v_cmp_gt_u32_e64 s[8:9], 32, v25
	v_or3_b32 v160, v13, v11, s23
	v_lshl_add_u64 v[140:141], s[2:3], 0, v[6:7]
	v_sub_u32_e32 v161, v2, v15
	v_sub_u32_e32 v162, 0, v2
	v_mov_b32_e32 v2, v3
	v_mov_b32_e32 v4, v3
	v_mov_b32_e32 v6, v3
	v_mov_b32_e32 v8, v3
	v_mov_b32_e32 v9, v3
	v_mov_b32_e32 v10, v3
	v_mov_b32_e32 v11, v3
	v_mov_b32_e32 v12, v3
	v_mov_b32_e32 v13, v3
	v_mov_b32_e32 v14, v3
	v_mov_b32_e32 v15, v3
	v_mov_b64_e32 v[66:67], v[16:17]
	v_mov_b64_e32 v[50:51], v[16:17]
	v_mov_b64_e32 v[34:35], v[16:17]
	v_mov_b64_e32 v[64:65], v[14:15]
	v_mov_b64_e32 v[62:63], v[12:13]
	v_mov_b64_e32 v[60:61], v[10:11]
	v_mov_b64_e32 v[58:59], v[8:9]
	v_mov_b64_e32 v[56:57], v[6:7]
	v_mov_b64_e32 v[54:55], v[4:5]
	v_mov_b64_e32 v[52:53], v[2:3]
	v_mov_b64_e32 v[48:49], v[14:15]
	v_mov_b64_e32 v[46:47], v[12:13]
	v_mov_b64_e32 v[44:45], v[10:11]
	v_mov_b64_e32 v[42:43], v[8:9]
	v_mov_b64_e32 v[40:41], v[6:7]
	v_mov_b64_e32 v[38:39], v[4:5]
	v_mov_b64_e32 v[36:37], v[2:3]
	v_mov_b64_e32 v[32:33], v[14:15]
	v_mov_b64_e32 v[30:31], v[12:13]
	v_mov_b64_e32 v[28:29], v[10:11]
	v_mov_b64_e32 v[26:27], v[8:9]
	v_mov_b64_e32 v[24:25], v[6:7]
	v_mov_b64_e32 v[22:23], v[4:5]
	v_mov_b64_e32 v[20:21], v[2:3]
	v_mov_b64_e32 v[18:19], v[16:17]
	s_mov_b32 s0, 1
	s_mov_b32 s1, 0
	v_mov_b32_e32 v133, v132
	v_mov_b32_e32 v143, 0
	v_mov_b32_e32 v165, 0xf149f2ca
	v_mov_b64_e32 v[16:17], v[14:15]
	v_mov_b64_e32 v[14:15], v[12:13]
	v_mov_b64_e32 v[12:13], v[10:11]
	v_mov_b64_e32 v[10:11], v[8:9]
	v_mov_b64_e32 v[8:9], v[6:7]
	v_mov_b64_e32 v[6:7], v[4:5]
	v_mov_b64_e32 v[4:5], v[2:3]
	v_mov_b32_e32 v226, 0
	v_mul_f32_e32 v227, 0x40faf232, v132
	v_mul_f32_e32 v228, 0x417af232, v132
	v_mul_f32_e32 v229, 0x41bc35a6, v132
	v_mul_f32_e32 v230, 0x427af232, v132
	v_mul_f32_e32 v231, 0x428d283c, v132
	v_mul_f32_e32 v232, 0x429cd760, v132
	v_mul_f32_e32 v233, 0x42ac8683, v132
	v_mul_f32_e32 v234, 0x42faf232, v132
	v_mul_f32_e32 v235, 0x430550ab, v132
	v_mul_f32_e32 v236, 0x430d283c, v132
	v_mul_f32_e32 v237, 0x4314ffce, v132
	v_mul_f32_e32 v238, 0x433c35a6, v132
	v_mul_f32_e32 v239, 0x43440d37, v132
	v_mul_f32_e32 v240, 0x434be4c9, v132
	v_mul_f32_e32 v241, 0x4353bc5b, v132
	s_branch .LBB0_342

; #define KSWZ(row, colB) ((row) * 256 + ((colB) ^ (KSWZF(row) << 4)))
; #define SBAR() __builtin_amdgcn_sched_barrier(0)
; template <int H> __device__ __forceinline__ void qkt_half(f32x16& pz, const char* Ks, const bf16x8* qr, int r32, int hi) {
;   bf16x8 kf[8];
; #pragma unroll
;   for (int d0 = 0; d0 < 8; ++d0) { const int cb = (d0 * 16 + hi * 8) * 2; kf[d0] = *reinterpret_cast<const bf16x8*>(Ks + KSWZ(32 * H + r32, cb)); }
;   asm volatile("s_waitcnt lgkmcnt(0)" ::: "memory"); SBAR();
;   f32x16 pb = {};
; #pragma unroll
;   for (int d0 = 0; d0 < 8; d0 += 2) {
;     pz = __builtin_amdgcn_mfma_f32_32x32x16_bf16(kf[d0], qr[d0], pz, 0, 0, 0);
;     pb = __builtin_amdgcn_mfma_f32_32x32x16_bf16(kf[d0 + 1], qr[d0 + 1], pb, 0, 0, 0); }
; template <int MODE>
; __device__ __forceinline__ void nsa_single(const Params& p, const LaneId& L, int q0, int g, int ntiles, int first, char* smem, const bf16x8* qr, float gate, f32x16* o) {
;     ...
;     else { lo = L.tq - 512 - pb; hl = L.tq - pb; }
;     constexpr float C = 0.08838834764831845f * LOG2E;
;     const float A1 = L.sl2; const float B1 = L.sl2 * (float)(pb - L.tq) + A1 * (float)(4 * L.hi) + badd;
;     const int lo2 = lo - 4 * L.hi, hl2 = hl - 4 * L.hi;
;     const bool nomask = __all(lo2 < 0 && hl2 >= 63);
.LBB0_344:
	v_add_u32_e32 v163, 0xfffffe00, v161
	v_cmp_lt_i32_e32 vcc, 62, v161
	v_cmp_gt_i32_e64 s[12:13], 0, v163
	v_cvt_f32_i32_e32 v2, v162
	s_nop 3
	s_and_b64 vcc, s[12:13], vcc
	s_cmp_lg_u64 vcc, exec
	s_cselect_b64 s[98:99], -1, 0
	v_fma_f32 v2, v132, v2, v150
	v_add_u32_e32 v248, s22, v151
	v_add_u32_e32 v249, v248, v152
	ds_read_b128 v[84:87], v249
	v_add_u32_e32 v251, v248, v153
	ds_read_b128 v[88:91], v251
	v_add_u32_e32 v249, v248, v154
	ds_read_b128 v[92:95], v249
	v_add_u32_e32 v251, v248, v155
	ds_read_b128 v[96:99], v251
	v_add_u32_e32 v249, v248, v156
	ds_read_b128 v[194:197], v249
	v_add_u32_e32 v251, v248, v157
	ds_read_b128 v[198:201], v251
	v_add_u32_e32 v249, v248, v158
	ds_read_b128 v[202:205], v249
	v_add_u32_e32 v251, v248, v159
	ds_read_b128 v[206:209], v251
	s_nop 0
	v_add_u32_e32 v248, s22, v160
	v_mov_b32_e32 v250, v2
	v_add_f32_e32 v243, 0x41000000, v165
	s_waitcnt lgkmcnt(0)
	v_mfma_f32_32x32x16_bf16 v[68:83], v[84:87], v[100:103], v[226:241]
	v_mfma_f32_32x32x16_bf16 v[68:83], v[88:91], v[104:107], v[68:83]
	v_mfma_f32_32x32x16_bf16 v[68:83], v[92:95], v[108:111], v[68:83]
	v_mfma_f32_32x32x16_bf16 v[68:83], v[96:99], v[112:115], v[68:83]
	v_mfma_f32_32x32x16_bf16 v[68:83], v[194:197], v[116:119], v[68:83]
	v_mfma_f32_32x32x16_bf16 v[68:83], v[198:201], v[120:123], v[68:83]
	v_mfma_f32_32x32x16_bf16 v[68:83], v[202:205], v[124:127], v[68:83]
	v_mfma_f32_32x32x16_bf16 v[68:83], v[206:209], v[128:131], v[68:83]
	ds_read_b64_tr_b16 v[84:85], v248 offset:0
	ds_read_b64_tr_b16 v[86:87], v248 offset:2048
	ds_read_b64_tr_b16 v[88:89], v248 offset:4096
	ds_read_b64_tr_b16 v[90:91], v248 offset:6144
	ds_read_b64_tr_b16 v[92:93], v248 offset:512
	ds_read_b64_tr_b16 v[94:95], v248 offset:2560
	ds_read_b64_tr_b16 v[96:97], v248 offset:4608
	ds_read_b64_tr_b16 v[98:99], v248 offset:6656
	ds_read_b64_tr_b16 v[194:195], v248 offset:1024
	ds_read_b64_tr_b16 v[196:197], v248 offset:3072
	ds_read_b64_tr_b16 v[198:199], v248 offset:5120
	ds_read_b64_tr_b16 v[200:201], v248 offset:7168
	ds_read_b64_tr_b16 v[202:203], v248 offset:1536
	ds_read_b64_tr_b16 v[204:205], v248 offset:3584
	ds_read_b64_tr_b16 v[206:207], v248 offset:5632
	ds_read_b64_tr_b16 v[208:209], v248 offset:7680
	s_and_b64 vcc, exec, s[98:99]
	s_cbranch_vccz .Lwin_nm0
	v_cmp_lt_i32_e32 vcc, -1, v161
	v_cmp_lt_i32_e64 s[10:11], 0, v161
	v_cmp_lt_i32_e64 s[12:13], 1, v161
	v_cmp_lt_i32_e64 s[2:3], 2, v161
	s_nop 0
	v_cndmask_b32_e32 v68, v183, v68, vcc
	v_cndmask_b32_e64 v69, v183, v69, s[10:11]
	v_cndmask_b32_e64 v70, v183, v70, s[12:13]
	v_cndmask_b32_e64 v71, v183, v71, s[2:3]
	v_cmp_lt_i32_e32 vcc, 7, v161
	v_cmp_lt_i32_e64 s[10:11], 8, v161
	v_cmp_lt_i32_e64 s[12:13], 9, v161
	v_cmp_lt_i32_e64 s[2:3], 10, v161
	s_nop 0
	v_cndmask_b32_e32 v72, v183, v72, vcc
	v_cndmask_b32_e64 v73, v183, v73, s[10:11]
	v_cndmask_b32_e64 v74, v183, v74, s[12:13]
	v_cndmask_b32_e64 v75, v183, v75, s[2:3]
	v_cmp_lt_i32_e32 vcc, 15, v161
	v_cmp_lt_i32_e64 s[10:11], 16, v161
	v_cmp_lt_i32_e64 s[12:13], 17, v161
	v_cmp_lt_i32_e64 s[2:3], 18, v161
	s_nop 0
	v_cndmask_b32_e32 v76, v183, v76, vcc
	v_cndmask_b32_e64 v77, v183, v77, s[10:11]
	v_cndmask_b32_e64 v78, v183, v78, s[12:13]
	v_cndmask_b32_e64 v79, v183, v79, s[2:3]
	v_cmp_lt_i32_e32 vcc, 23, v161
	v_cmp_lt_i32_e64 s[10:11], 24, v161
	v_cmp_lt_i32_e64 s[12:13], 25, v161
	v_cmp_lt_i32_e64 s[2:3], 26, v161
	s_nop 0
	v_cndmask_b32_e32 v80, v183, v80, vcc
	v_cndmask_b32_e64 v81, v183, v81, s[10:11]
	v_cndmask_b32_e64 v82, v183, v82, s[12:13]
	v_cndmask_b32_e64 v83, v183, v83, s[2:3]
	v_cmp_gt_i32_e32 vcc, 0, v163
	v_cmp_gt_i32_e64 s[10:11], 1, v163
	v_cmp_gt_i32_e64 s[12:13], 2, v163
	v_cmp_gt_i32_e64 s[2:3], 3, v163
	s_nop 0
	v_cndmask_b32_e32 v68, v183, v68, vcc
	v_cndmask_b32_e64 v69, v183, v69, s[10:11]
	v_cndmask_b32_e64 v70, v183, v70, s[12:13]
	v_cndmask_b32_e64 v71, v183, v71, s[2:3]
	v_cmp_gt_i32_e32 vcc, 8, v163
	v_cmp_gt_i32_e64 s[10:11], 9, v163
	v_cmp_gt_i32_e64 s[12:13], 10, v163
	v_cmp_gt_i32_e64 s[2:3], 11, v163
	s_nop 0
	v_cndmask_b32_e32 v72, v183, v72, vcc
	v_cndmask_b32_e64 v73, v183, v73, s[10:11]
	v_cndmask_b32_e64 v74, v183, v74, s[12:13]
	v_cndmask_b32_e64 v75, v183, v75, s[2:3]
	v_cmp_gt_i32_e32 vcc, 16, v163
	v_cmp_gt_i32_e64 s[10:11], 17, v163
	v_cmp_gt_i32_e64 s[12:13], 18, v163
	v_cmp_gt_i32_e64 s[2:3], 19, v163
	s_nop 0
	v_cndmask_b32_e32 v76, v183, v76, vcc
	v_cndmask_b32_e64 v77, v183, v77, s[10:11]
	v_cndmask_b32_e64 v78, v183, v78, s[12:13]
	v_cndmask_b32_e64 v79, v183, v79, s[2:3]
	v_cmp_gt_i32_e32 vcc, 24, v163
	v_cmp_gt_i32_e64 s[10:11], 25, v163
	v_cmp_gt_i32_e64 s[12:13], 26, v163
	v_cmp_gt_i32_e64 s[2:3], 27, v163
	s_nop 0
	v_cndmask_b32_e32 v80, v183, v80, vcc
	v_cndmask_b32_e64 v81, v183, v81, s[10:11]
	v_cndmask_b32_e64 v82, v183, v82, s[12:13]
	v_cndmask_b32_e64 v83, v183, v83, s[2:3]
.Lwin_nm0:
	v_max3_f32 v244, v68, v69, v70
	v_max3_f32 v244, v244, v71, v72
	v_max3_f32 v244, v244, v73, v74
	v_max3_f32 v244, v244, v75, v76
	v_max3_f32 v244, v244, v77, v78
	v_max3_f32 v244, v244, v79, v80
	v_max3_f32 v244, v244, v81, v82
	v_max_f32_e32 v244, v244, v83
	v_fmamk_f32 v246, v244, 0x3e0293ee, v250
	v_mov_b32_e32 v245, v246
	s_nop 1
	v_permlane32_swap_b32_e32 v246, v245
	v_max_f32_e32 v246, v246, v245
	v_cmp_gt_f32_e32 vcc, v246, v243
	s_cbranch_vccz .Lwin_nr0
	v_max_f32_e32 v246, v246, v165
	v_sub_f32_e32 v247, v165, v246
	v_exp_f32_e32 v247, v247
	v_mov_b32_e32 v165, v246
	s_and_saveexec_b64 s[2:3], s[8:9]
	ds_write_b32 v148, v247
	s_or_b64 exec, exec, s[2:3]
	v_mul_f32_e32 v143, v143, v247
	ds_read_b128 v[168:171], v147
	ds_read_b128 v[172:175], v147 offset:32
	ds_read_b128 v[242:245], v147 offset:64
	ds_read_b128 v[246:249], v147 offset:96
	s_waitcnt lgkmcnt(0)
	v_mul_f32_e32 v52, v52, v168
	v_mul_f32_e32 v53, v53, v169
	v_mul_f32_e32 v54, v54, v170
	v_mul_f32_e32 v55, v55, v171
	v_mul_f32_e32 v56, v56, v172
	v_mul_f32_e32 v57, v57, v173
	v_mul_f32_e32 v58, v58, v174
	v_mul_f32_e32 v59, v59, v175
	v_mul_f32_e32 v60, v60, v242
	v_mul_f32_e32 v61, v61, v243
	v_mul_f32_e32 v62, v62, v244
	v_mul_f32_e32 v63, v63, v245
	v_mul_f32_e32 v64, v64, v246
	v_mul_f32_e32 v65, v65, v247
	v_mul_f32_e32 v66, v66, v248
	v_mul_f32_e32 v67, v67, v249
	v_mul_f32_e32 v36, v36, v168
	v_mul_f32_e32 v37, v37, v169
	v_mul_f32_e32 v38, v38, v170
	v_mul_f32_e32 v39, v39, v171
	v_mul_f32_e32 v40, v40, v172
	v_mul_f32_e32 v41, v41, v173
	v_mul_f32_e32 v42, v42, v174
	v_mul_f32_e32 v43, v43, v175
	v_mul_f32_e32 v44, v44, v242
	v_mul_f32_e32 v45, v45, v243
	v_mul_f32_e32 v46, v46, v244
	v_mul_f32_e32 v47, v47, v245
	v_mul_f32_e32 v48, v48, v246
	v_mul_f32_e32 v49, v49, v247
	v_mul_f32_e32 v50, v50, v248
	v_mul_f32_e32 v51, v51, v249
	v_mul_f32_e32 v20, v20, v168
	v_mul_f32_e32 v21, v21, v169
	v_mul_f32_e32 v22, v22, v170
	v_mul_f32_e32 v23, v23, v171
	v_mul_f32_e32 v24, v24, v172
	v_mul_f32_e32 v25, v25, v173
	v_mul_f32_e32 v26, v26, v174
	v_mul_f32_e32 v27, v27, v175
	v_mul_f32_e32 v28, v28, v242
	v_mul_f32_e32 v29, v29, v243
	v_mul_f32_e32 v30, v30, v244
	v_mul_f32_e32 v31, v31, v245
	v_mul_f32_e32 v32, v32, v246
	v_mul_f32_e32 v33, v33, v247
	v_mul_f32_e32 v34, v34, v248
	v_mul_f32_e32 v35, v35, v249
	v_mul_f32_e32 v4, v4, v168
	v_mul_f32_e32 v5, v5, v169
	v_mul_f32_e32 v6, v6, v170
	v_mul_f32_e32 v7, v7, v171
	v_mul_f32_e32 v8, v8, v172
	v_mul_f32_e32 v9, v9, v173
	v_mul_f32_e32 v10, v10, v174
	v_mul_f32_e32 v11, v11, v175
	v_mul_f32_e32 v12, v12, v242
	v_mul_f32_e32 v13, v13, v243
	v_mul_f32_e32 v14, v14, v244
	v_mul_f32_e32 v15, v15, v245
	v_mul_f32_e32 v16, v16, v246
	v_mul_f32_e32 v17, v17, v247
	v_mul_f32_e32 v18, v18, v248
	v_mul_f32_e32 v19, v19, v249
.Lwin_nr0:
	v_sub_f32_e32 v251, v250, v165
	s_nop 0
	v_fmamk_f32 v68, v68, 0x3e0293ee, v251
	v_fmamk_f32 v69, v69, 0x3e0293ee, v251
	v_fmamk_f32 v70, v70, 0x3e0293ee, v251
	v_fmamk_f32 v71, v71, 0x3e0293ee, v251
	v_fmamk_f32 v72, v72, 0x3e0293ee, v251
	v_fmamk_f32 v73, v73, 0x3e0293ee, v251
	v_fmamk_f32 v74, v74, 0x3e0293ee, v251
	v_fmamk_f32 v75, v75, 0x3e0293ee, v251
	v_fmamk_f32 v76, v76, 0x3e0293ee, v251
	v_fmamk_f32 v77, v77, 0x3e0293ee, v251
	v_fmamk_f32 v78, v78, 0x3e0293ee, v251
	v_fmamk_f32 v79, v79, 0x3e0293ee, v251
	v_fmamk_f32 v80, v80, 0x3e0293ee, v251
	v_fmamk_f32 v81, v81, 0x3e0293ee, v251
	v_fmamk_f32 v82, v82, 0x3e0293ee, v251
	v_fmamk_f32 v83, v83, 0x3e0293ee, v251
	v_exp_f32_e32 v68, v68
	v_exp_f32_e32 v69, v69
	v_exp_f32_e32 v70, v70
	v_exp_f32_e32 v71, v71
	v_exp_f32_e32 v72, v72
	v_exp_f32_e32 v73, v73
	v_exp_f32_e32 v74, v74
	v_exp_f32_e32 v75, v75
	v_exp_f32_e32 v76, v76
	v_exp_f32_e32 v77, v77
	v_exp_f32_e32 v78, v78
	v_exp_f32_e32 v79, v79
	v_exp_f32_e32 v80, v80
	v_exp_f32_e32 v81, v81
	v_exp_f32_e32 v82, v82
	v_exp_f32_e32 v83, v83
	s_nop 0
	v_add_f32_e32 v246, v68, v69
	v_add_f32_e32 v247, v70, v71
	v_add_f32_e32 v246, v246, v72
	v_add_f32_e32 v246, v246, v73
	v_add_f32_e32 v247, v247, v74
	v_add_f32_e32 v247, v247, v75
	v_add_f32_e32 v246, v246, v76
	v_add_f32_e32 v246, v246, v77
	v_add_f32_e32 v247, v247, v78
	v_add_f32_e32 v247, v247, v79
	v_add_f32_e32 v246, v246, v80
	v_add_f32_e32 v246, v246, v81
	v_add_f32_e32 v247, v247, v82
	v_add_f32_e32 v247, v247, v83
	v_add_f32_e32 v246, v246, v247
	v_add_f32_e32 v143, v143, v246
	v_cvt_pk_bf16_f32 v168, v68, v69
	v_cvt_pk_bf16_f32 v169, v70, v71
	v_cvt_pk_bf16_f32 v170, v72, v73
	v_cvt_pk_bf16_f32 v171, v74, v75
	v_cvt_pk_bf16_f32 v172, v76, v77
	v_cvt_pk_bf16_f32 v173, v78, v79
	v_cvt_pk_bf16_f32 v174, v80, v81
	v_cvt_pk_bf16_f32 v175, v82, v83
	s_waitcnt lgkmcnt(0)
; template <int H> __device__ __forceinline__ void qkt_half(f32x16& pz, const char* Ks, const bf16x8* qr, int r32, int hi) {
;   bf16x8 kf[8];
; #pragma unroll
;   for (int d0 = 0; d0 < 8; ++d0) { const int cb = (d0 * 16 + hi * 8) * 2; kf[d0] = *reinterpret_cast<const bf16x8*>(Ks + KSWZ(32 * H + r32, cb)); }
;   asm volatile("s_waitcnt lgkmcnt(0)" ::: "memory"); SBAR();
;   f32x16 pb = {};
; #pragma unroll
;   for (int d0 = 0; d0 < 8; d0 += 2) {
;     pz = __builtin_amdgcn_mfma_f32_32x32x16_bf16(kf[d0], qr[d0], pz, 0, 0, 0);
;     pb = __builtin_amdgcn_mfma_f32_32x32x16_bf16(kf[d0 + 1], qr[d0 + 1], pb, 0, 0, 0); }
; #pragma unroll
;   for (int r = 0; r < 16; ++r) pz[r] += pb[r];
; }
; template <bool MASK, int H> __device__ __forceinline__ void bias_exp_half(f32x16& pz, float C, float A1, float B1, int lo, int hl, float off) {
; #pragma unroll
;   for (int r = 0; r < 16; ++r) {
;     const int c0 = (r & 3) + 8 * (r >> 2) + 32 * H;
;     float s0 = fmaf(pz[r], C, fmaf(A1, (float)c0, B1)) - off;
;     if (MASK) s0 = (c0 > lo && c0 <= hl) ? s0 : -INFINITY;
;     pz[r] = __builtin_amdgcn_exp2f(s0);
;   }
; }
; __device__ __forceinline__ void pack_half(const f32x16& pz, bf16x8& paA, bf16x8& paB) {
;     ...
;   PK4(pz, 0, paA); PK4(pz, 8, paB);
;     ...
; }
; template <int H> __device__ __forceinline__ void pv_half(f32x16* o, int vb, bf16x8 paA, bf16x8 paB) {
;     ...
;   TRQ(0); TRQ(1); TRQ(2); TRQ(3);
;     ...
;   asm volatile("s_waitcnt lgkmcnt(0)" ::: "memory"); SBAR();
;     ...
;   o[0] = __builtin_amdgcn_mfma_f32_32x32x16_bf16(paA, PK(l0_0, h0_0), o[0], 0, 0, 0);
;   o[1] = __builtin_amdgcn_mfma_f32_32x32x16_bf16(paA, PK(l0_1, h0_1), o[1], 0, 0, 0);
;   o[2] = __builtin_amdgcn_mfma_f32_32x32x16_bf16(paA, PK(l0_2, h0_2), o[2], 0, 0, 0);
;   o[3] = __builtin_amdgcn_mfma_f32_32x32x16_bf16(paA, PK(l0_3, h0_3), o[3], 0, 0, 0);
;   o[0] = __builtin_amdgcn_mfma_f32_32x32x16_bf16(paB, PK(l1_0, h1_0), o[0], 0, 0, 0);
;   o[1] = __builtin_amdgcn_mfma_f32_32x32x16_bf16(paB, PK(l1_1, h1_1), o[1], 0, 0, 0);
;   o[2] = __builtin_amdgcn_mfma_f32_32x32x16_bf16(paB, PK(l1_2, h1_2), o[2], 0, 0, 0);
;   o[3] = __builtin_amdgcn_mfma_f32_32x32x16_bf16(paB, PK(l1_3, h1_3), o[3], 0, 0, 0);
;     ...
; }
; template <int MODE>
; __device__ __forceinline__ void nsa_single(const Params& p, const LaneId& L, int q0, int g, int ntiles, int first, char* smem, const bf16x8* qr, float gate, f32x16* o) {
;     ...
;     NSA_SHALF(0);
;     NSA_SHALF(1);
	s_nop 1
	v_permlane32_swap_b32_e32 v168, v170
	v_permlane32_swap_b32_e32 v169, v171
	v_permlane32_swap_b32_e32 v172, v174
	v_permlane32_swap_b32_e32 v173, v175
	s_nop 1
	v_mfma_f32_32x32x16_bf16 v[52:67], v[168:171], v[84:87], v[52:67]
	v_mfma_f32_32x32x16_bf16 v[36:51], v[168:171], v[92:95], v[36:51]
	v_mfma_f32_32x32x16_bf16 v[20:35], v[168:171], v[194:197], v[20:35]
	v_mfma_f32_32x32x16_bf16 v[4:19], v[168:171], v[202:205], v[4:19]
	v_mfma_f32_32x32x16_bf16 v[52:67], v[172:175], v[88:91], v[52:67]
	v_mfma_f32_32x32x16_bf16 v[36:51], v[172:175], v[96:99], v[36:51]
	v_mfma_f32_32x32x16_bf16 v[20:35], v[172:175], v[198:201], v[20:35]
	v_mfma_f32_32x32x16_bf16 v[4:19], v[172:175], v[206:209], v[4:19]
	v_add_u32_e32 v248, s22, v151
	v_add_u32_e32 v249, v248, v152
	ds_read_b128 v[84:87], v249 offset:8192
	v_add_u32_e32 v251, v248, v153
	ds_read_b128 v[88:91], v251 offset:8192
	v_add_u32_e32 v249, v248, v154
	ds_read_b128 v[92:95], v249 offset:8192
	v_add_u32_e32 v251, v248, v155
	ds_read_b128 v[96:99], v251 offset:8192
	v_add_u32_e32 v249, v248, v156
	ds_read_b128 v[194:197], v249 offset:8192
	v_add_u32_e32 v251, v248, v157
	ds_read_b128 v[198:201], v251 offset:8192
	v_add_u32_e32 v249, v248, v158
	ds_read_b128 v[202:205], v249 offset:8192
	v_add_u32_e32 v251, v248, v159
	ds_read_b128 v[206:209], v251 offset:8192
	s_nop 0
	v_add_u32_e32 v248, s22, v160
	v_fmamk_f32 v250, v132, 0x42000000, v2
	v_add_f32_e32 v243, 0x41000000, v165
	s_waitcnt lgkmcnt(0)
	v_mfma_f32_32x32x16_bf16 v[68:83], v[84:87], v[100:103], v[226:241]
	v_mfma_f32_32x32x16_bf16 v[68:83], v[88:91], v[104:107], v[68:83]
	v_mfma_f32_32x32x16_bf16 v[68:83], v[92:95], v[108:111], v[68:83]
	v_mfma_f32_32x32x16_bf16 v[68:83], v[96:99], v[112:115], v[68:83]
	v_mfma_f32_32x32x16_bf16 v[68:83], v[194:197], v[116:119], v[68:83]
	v_mfma_f32_32x32x16_bf16 v[68:83], v[198:201], v[120:123], v[68:83]
	v_mfma_f32_32x32x16_bf16 v[68:83], v[202:205], v[124:127], v[68:83]
	v_mfma_f32_32x32x16_bf16 v[68:83], v[206:209], v[128:131], v[68:83]
	ds_read_b64_tr_b16 v[84:85], v248 offset:8192
	ds_read_b64_tr_b16 v[86:87], v248 offset:10240
	ds_read_b64_tr_b16 v[88:89], v248 offset:12288
	ds_read_b64_tr_b16 v[90:91], v248 offset:14336
	ds_read_b64_tr_b16 v[92:93], v248 offset:8704
	ds_read_b64_tr_b16 v[94:95], v248 offset:10752
	ds_read_b64_tr_b16 v[96:97], v248 offset:12800
	ds_read_b64_tr_b16 v[98:99], v248 offset:14848
	ds_read_b64_tr_b16 v[194:195], v248 offset:9216
	ds_read_b64_tr_b16 v[196:197], v248 offset:11264
	ds_read_b64_tr_b16 v[198:199], v248 offset:13312
	ds_read_b64_tr_b16 v[200:201], v248 offset:15360
	ds_read_b64_tr_b16 v[202:203], v248 offset:9728
	ds_read_b64_tr_b16 v[204:205], v248 offset:11776
	ds_read_b64_tr_b16 v[206:207], v248 offset:13824
	ds_read_b64_tr_b16 v[208:209], v248 offset:15872
	s_and_b64 vcc, exec, s[98:99]
	s_cbranch_vccz .Lwin_nm1
	v_cmp_lt_i32_e32 vcc, 31, v161
	v_cmp_lt_i32_e64 s[10:11], 32, v161
	v_cmp_lt_i32_e64 s[12:13], 33, v161
	v_cmp_lt_i32_e64 s[2:3], 34, v161
	s_nop 0
	v_cndmask_b32_e32 v68, v183, v68, vcc
	v_cndmask_b32_e64 v69, v183, v69, s[10:11]
	v_cndmask_b32_e64 v70, v183, v70, s[12:13]
	v_cndmask_b32_e64 v71, v183, v71, s[2:3]
	v_cmp_lt_i32_e32 vcc, 39, v161
	v_cmp_lt_i32_e64 s[10:11], 40, v161
	v_cmp_lt_i32_e64 s[12:13], 41, v161
	v_cmp_lt_i32_e64 s[2:3], 42, v161
	s_nop 0
	v_cndmask_b32_e32 v72, v183, v72, vcc
	v_cndmask_b32_e64 v73, v183, v73, s[10:11]
	v_cndmask_b32_e64 v74, v183, v74, s[12:13]
	v_cndmask_b32_e64 v75, v183, v75, s[2:3]
	v_cmp_lt_i32_e32 vcc, 47, v161
	v_cmp_lt_i32_e64 s[10:11], 48, v161
	v_cmp_lt_i32_e64 s[12:13], 49, v161
	v_cmp_lt_i32_e64 s[2:3], 50, v161
	s_nop 0
	v_cndmask_b32_e32 v76, v183, v76, vcc
	v_cndmask_b32_e64 v77, v183, v77, s[10:11]
	v_cndmask_b32_e64 v78, v183, v78, s[12:13]
	v_cndmask_b32_e64 v79, v183, v79, s[2:3]
	v_cmp_lt_i32_e32 vcc, 55, v161
	v_cmp_lt_i32_e64 s[10:11], 56, v161
	v_cmp_lt_i32_e64 s[12:13], 57, v161
	v_cmp_lt_i32_e64 s[2:3], 58, v161
	s_nop 0
	v_cndmask_b32_e32 v80, v183, v80, vcc
	v_cndmask_b32_e64 v81, v183, v81, s[10:11]
	v_cndmask_b32_e64 v82, v183, v82, s[12:13]
	v_cndmask_b32_e64 v83, v183, v83, s[2:3]
	v_cmp_gt_i32_e32 vcc, 32, v163
	v_cmp_gt_i32_e64 s[10:11], 33, v163
	v_cmp_gt_i32_e64 s[12:13], 34, v163
	v_cmp_gt_i32_e64 s[2:3], 35, v163
	s_nop 0
	v_cndmask_b32_e32 v68, v183, v68, vcc
	v_cndmask_b32_e64 v69, v183, v69, s[10:11]
	v_cndmask_b32_e64 v70, v183, v70, s[12:13]
	v_cndmask_b32_e64 v71, v183, v71, s[2:3]
	v_cmp_gt_i32_e32 vcc, 40, v163
	v_cmp_gt_i32_e64 s[10:11], 41, v163
	v_cmp_gt_i32_e64 s[12:13], 42, v163
	v_cmp_gt_i32_e64 s[2:3], 43, v163
	s_nop 0
	v_cndmask_b32_e32 v72, v183, v72, vcc
	v_cndmask_b32_e64 v73, v183, v73, s[10:11]
	v_cndmask_b32_e64 v74, v183, v74, s[12:13]
	v_cndmask_b32_e64 v75, v183, v75, s[2:3]
	v_cmp_gt_i32_e32 vcc, 48, v163
	v_cmp_gt_i32_e64 s[10:11], 49, v163
	v_cmp_gt_i32_e64 s[12:13], 50, v163
	v_cmp_gt_i32_e64 s[2:3], 51, v163
	s_nop 0
	v_cndmask_b32_e32 v76, v183, v76, vcc
	v_cndmask_b32_e64 v77, v183, v77, s[10:11]
	v_cndmask_b32_e64 v78, v183, v78, s[12:13]
	v_cndmask_b32_e64 v79, v183, v79, s[2:3]
	v_cmp_gt_i32_e32 vcc, 56, v163
	v_cmp_gt_i32_e64 s[10:11], 57, v163
	v_cmp_gt_i32_e64 s[12:13], 58, v163
	v_cmp_gt_i32_e64 s[2:3], 59, v163
	s_nop 0
	v_cndmask_b32_e32 v80, v183, v80, vcc
	v_cndmask_b32_e64 v81, v183, v81, s[10:11]
	v_cndmask_b32_e64 v82, v183, v82, s[12:13]
	v_cndmask_b32_e64 v83, v183, v83, s[2:3]

; #define SBAR() __builtin_amdgcn_sched_barrier(0)
; #define TRQ(D0) const s16x4 l0_##D0 = tr_read<v_rd_off(D0, 2 * H, 0)>(vb), h0_##D0 = tr_read<v_rd_off(D0, 2 * H, 1)>(vb), \
;                             l1_##D0 = tr_read<v_rd_off(D0, 2 * H + 1, 0)>(vb), h1_##D0 = tr_read<v_rd_off(D0, 2 * H + 1, 1)>(vb)
; template <int H> __device__ __forceinline__ void pv_half(f32x16* o, int vb, bf16x8 paA, bf16x8 paB) {
;     ...
;   TRQ(0); TRQ(1); TRQ(2); TRQ(3);
;     ...
;   asm volatile("s_waitcnt lgkmcnt(0)" ::: "memory"); SBAR();
;     ...
;   o[0] = __builtin_amdgcn_mfma_f32_32x32x16_bf16(paA, PK(l0_0, h0_0), o[0], 0, 0, 0);
;   o[1] = __builtin_amdgcn_mfma_f32_32x32x16_bf16(paA, PK(l0_1, h0_1), o[1], 0, 0, 0);
;   o[2] = __builtin_amdgcn_mfma_f32_32x32x16_bf16(paA, PK(l0_2, h0_2), o[2], 0, 0, 0);
;   o[3] = __builtin_amdgcn_mfma_f32_32x32x16_bf16(paA, PK(l0_3, h0_3), o[3], 0, 0, 0);
;   o[0] = __builtin_amdgcn_mfma_f32_32x32x16_bf16(paB, PK(l1_0, h1_0), o[0], 0, 0, 0);
;   o[1] = __builtin_amdgcn_mfma_f32_32x32x16_bf16(paB, PK(l1_1, h1_1), o[1], 0, 0, 0);
;   o[2] = __builtin_amdgcn_mfma_f32_32x32x16_bf16(paB, PK(l1_2, h1_2), o[2], 0, 0, 0);
;   o[3] = __builtin_amdgcn_mfma_f32_32x32x16_bf16(paB, PK(l1_3, h1_3), o[3], 0, 0, 0);
;     ...
; }
; template <int MODE>
; __device__ __forceinline__ void nsa_single(const Params& p, const LaneId& L, int q0, int g, int ntiles, int first, char* smem, const bf16x8* qr, float gate, f32x16* o) {
;     ...
;     NSA_SHALF(0);
;     NSA_SHALF(1);
;     ...
;   }
.Lwin_nr1:
	v_sub_f32_e32 v251, v250, v165
	s_nop 0
	v_fmamk_f32 v68, v68, 0x3e0293ee, v251
	v_fmamk_f32 v69, v69, 0x3e0293ee, v251
	v_fmamk_f32 v70, v70, 0x3e0293ee, v251
	v_fmamk_f32 v71, v71, 0x3e0293ee, v251
	v_fmamk_f32 v72, v72, 0x3e0293ee, v251
	v_fmamk_f32 v73, v73, 0x3e0293ee, v251
	v_fmamk_f32 v74, v74, 0x3e0293ee, v251
	v_fmamk_f32 v75, v75, 0x3e0293ee, v251
	v_fmamk_f32 v76, v76, 0x3e0293ee, v251
	v_fmamk_f32 v77, v77, 0x3e0293ee, v251
	v_fmamk_f32 v78, v78, 0x3e0293ee, v251
	v_fmamk_f32 v79, v79, 0x3e0293ee, v251
	v_fmamk_f32 v80, v80, 0x3e0293ee, v251
	v_fmamk_f32 v81, v81, 0x3e0293ee, v251
	v_fmamk_f32 v82, v82, 0x3e0293ee, v251
	v_fmamk_f32 v83, v83, 0x3e0293ee, v251
	v_exp_f32_e32 v68, v68
	v_exp_f32_e32 v69, v69
	v_exp_f32_e32 v70, v70
	v_exp_f32_e32 v71, v71
	v_exp_f32_e32 v72, v72
	v_exp_f32_e32 v73, v73
	v_exp_f32_e32 v74, v74
	v_exp_f32_e32 v75, v75
	v_exp_f32_e32 v76, v76
	v_exp_f32_e32 v77, v77
	v_exp_f32_e32 v78, v78
	v_exp_f32_e32 v79, v79
	v_exp_f32_e32 v80, v80
	v_exp_f32_e32 v81, v81
	v_exp_f32_e32 v82, v82
	v_exp_f32_e32 v83, v83
	s_nop 0
	v_add_f32_e32 v246, v68, v69
	v_add_f32_e32 v247, v70, v71
	v_add_f32_e32 v246, v246, v72
	v_add_f32_e32 v246, v246, v73
	v_add_f32_e32 v247, v247, v74
	v_add_f32_e32 v247, v247, v75
	v_add_f32_e32 v246, v246, v76
	v_add_f32_e32 v246, v246, v77
	v_add_f32_e32 v247, v247, v78
	v_add_f32_e32 v247, v247, v79
	v_add_f32_e32 v246, v246, v80
	v_add_f32_e32 v246, v246, v81
	v_add_f32_e32 v247, v247, v82
	v_add_f32_e32 v247, v247, v83
	v_add_f32_e32 v246, v246, v247
	v_add_f32_e32 v143, v143, v246
	v_cvt_pk_bf16_f32 v168, v68, v69
	v_cvt_pk_bf16_f32 v169, v70, v71
	v_cvt_pk_bf16_f32 v170, v72, v73
	v_cvt_pk_bf16_f32 v171, v74, v75
	v_cvt_pk_bf16_f32 v172, v76, v77
	v_cvt_pk_bf16_f32 v173, v78, v79
	v_cvt_pk_bf16_f32 v174, v80, v81
	v_cvt_pk_bf16_f32 v175, v82, v83
	s_waitcnt lgkmcnt(0)
	s_nop 1
	v_permlane32_swap_b32_e32 v168, v170
	v_permlane32_swap_b32_e32 v169, v171
	v_permlane32_swap_b32_e32 v172, v174
	v_permlane32_swap_b32_e32 v173, v175
	s_nop 1
	v_mfma_f32_32x32x16_bf16 v[52:67], v[168:171], v[84:87], v[52:67]
	v_mfma_f32_32x32x16_bf16 v[36:51], v[168:171], v[92:95], v[36:51]
	v_mfma_f32_32x32x16_bf16 v[20:35], v[168:171], v[194:197], v[20:35]
	v_mfma_f32_32x32x16_bf16 v[4:19], v[168:171], v[202:205], v[4:19]
	v_mfma_f32_32x32x16_bf16 v[52:67], v[172:175], v[88:91], v[52:67]
	v_mfma_f32_32x32x16_bf16 v[36:51], v[172:175], v[96:99], v[36:51]
	v_mfma_f32_32x32x16_bf16 v[20:35], v[172:175], v[198:201], v[20:35]
	v_mfma_f32_32x32x16_bf16 v[4:19], v[172:175], v[206:209], v[4:19]
	s_addk_i32 s1, 0x4000
	s_add_i32 s0, s0, 1
	v_lshl_add_u64 v[134:135], v[134:135], 0, s[20:21]
	v_lshl_add_u64 v[136:137], v[136:137], 0, s[20:21]
	v_lshl_add_u64 v[138:139], v[138:139], 0, s[20:21]
	v_lshl_add_u64 v[140:141], v[140:141], 0, s[20:21]
	v_add_u32_e32 v161, 64, v161
	v_subrev_u32_e32 v162, 64, v162
	s_cmp_eq_u32 s24, s1
	s_cbranch_scc1 .LBB0_361
	s_branch .LBB0_342
